# P0 mod GEMM: all w_ada row loads issued up front, silu(c) fragments stored tile-major so each fragment load is one contiguous 1 KiB read (was 16 half lines, an L2 hot spot)
# speedup vs baseline: 1.0516x; 1.0084x over previous
; __device__ __forceinline__ unsigned cvt_pk_bf16(float lo, float hi) { unsigned r; asm("v_cvt_pk_bf16_f32 %0, %1, %2" : "=v"(r) : "v"(lo), "v"(hi)); return r; }
; __device__ __forceinline__ float silu_f(float x) { return x * __builtin_amdgcn_rcpf(1.f + __expf(-x)); }
; __global__ __launch_bounds__(512, 2) void fwd_megakernel(Params p) {
;     ...
;       for (int i = bid * 512 + tid; i < 144 * DM / 8; i += G * 512) { const int b = i >> 7, k = (i & 127) * 8; uint4 o = {0u, 0u, 0u, 0u};
;           if (b < NB) { const float* cp = (b < 8 ? p.c_prompt + (size_t)b * DM : p.c_sample + (size_t)(b - 8) * DM) + k; const f32x4 c0 = *(const f32x4*)cp, c1 = *(const f32x4*)(cp + 4);
;               o.x = cvt_pk_bf16(silu_f(c0[0]), silu_f(c0[1])); o.y = cvt_pk_bf16(silu_f(c0[2]), silu_f(c0[3])); o.z = cvt_pk_bf16(silu_f(c1[0]), silu_f(c1[1])); o.w = cvt_pk_bf16(silu_f(c1[2]), silu_f(c1[3])); }
;           *(uint4*)(Sb + (size_t)b * DM + k) = o; }
.LBB0_7:
	s_or_b64 exec, exec, s[14:15]
	v_and_b32_e32 v8, 15, v12
	v_and_b32_e32 v12, -16, v12
	v_lshlrev_b64 v[12:13], 11, v[12:13]
	v_add_u32_e32 v11, s12, v11
	v_lshl_add_u64 v[12:13], s[4:5], 0, v[12:13]
	v_lshlrev_b32_e32 v8, 4, v8
	v_lshl_or_b32 v8, v10, 5, v8
	v_cmp_lt_i32_e32 vcc, s17, v11
	v_lshl_add_u64 v[12:13], v[12:13], 0, v[8:9]
	s_or_b64 s[10:11], vcc, s[10:11]
	v_add_u32_e32 v7, s13, v7
	global_store_dwordx4 v[12:13], v[2:5], off
	s_andn2_b64 exec, exec, s[10:11]
	s_cbranch_execz .LBB0_10

; __device__ __forceinline__ unsigned cvt_pk_bf16(float lo, float hi) { unsigned r; asm("v_cvt_pk_bf16_f32 %0, %1, %2" : "=v"(r) : "v"(lo), "v"(hi)); return r; }
; __device__ __forceinline__ int fresh_tid() { int t = threadIdx.x; asm volatile("" : "+v"(t)); return t; }
; __device__ __forceinline__ void mod_phase(const Params& p, const bf16_t* __restrict__ Sb, float* smem) {
;     const int tid = fresh_tid(), w = tid >> 6, lane = tid & 63, fr = lane & 15, fq = lane >> 4;
;     f32x4* red = (f32x4*)smem; float* mod = (float*)(p.ws + WS_MOD);
;     for (int it = blockIdx.x; it < NMOD / 32; it += gridDim.x) {
;         const int col0 = it * 32;
;         f32x4 acc[2][9];
; #pragma unroll
;         for (int i = 0; i < 9; ++i) { acc[0][i] = (f32x4){0.f, 0.f, 0.f, 0.f}; acc[1][i] = (f32x4){0.f, 0.f, 0.f, 0.f}; }
;         Frag wfA[4], wfB[4];
; #pragma unroll
;         for (int kk = 0; kk < 4; ++kk) { const float* wp = p.w_ada + (size_t)(w * 128 + kk * 32 + fq * 8) * NMOD + col0 + 2 * fr;
; #pragma unroll
;             for (int i = 0; i < 4; ++i) { const float2 v0 = *(const float2*)(wp + (size_t)(2 * i) * NMOD), v1 = *(const float2*)(wp + (size_t)(2 * i + 1) * NMOD);
;                 wfA[kk].u[i] = cvt_pk_bf16(v0.x, v1.x); wfB[kk].u[i] = cvt_pk_bf16(v0.y, v1.y); } }
; #pragma unroll
;         for (int kk = 0; kk < 4; ++kk) {
; #pragma unroll
;             for (int bt = 0; bt < 9; ++bt) { Frag sf; sf.q = *(const uint4*)(Sb + (size_t)(bt * 16 + fr) * DM + w * 128 + kk * 32 + fq * 8);
.LBB0_67:
	s_or_b64 exec, exec, s[6:7]
	s_add_u32 s16, s58, 0x1740000
	s_addc_u32 s17, s59, 0
	v_mov_b32_e32 v141, v224
	s_andn2_b64 vcc, exec, s[8:9]
	s_barrier
	s_cbranch_vccnz .LBB0_81
	v_ashrrev_i32_e32 v20, 6, v141
	v_lshlrev_b32_e32 v0, 7, v20
	v_lshrrev_b32_e32 v1, 1, v141
	v_and_b32_e32 v2, 24, v1
	v_ashrrev_i32_e32 v1, 31, v0
	v_and_b32_e32 v152, 15, v141
	v_or_b32_e32 v21, v0, v2
	v_lshl_add_u64 v[0:1], v[0:1], 1, s[4:5]
	v_lshlrev_b32_e32 v2, 1, v2
	v_mov_b32_e32 v3, 0
	v_lshl_add_u64 v[0:1], v[0:1], 0, v[2:3]
	v_lshlrev_b32_e32 v2, 11, v152
	v_lshl_add_u64 v[72:73], v[0:1], 0, v[2:3]
	v_or_b32_e32 v4, 0x8000, v2
	v_mov_b32_e32 v5, v3
	v_or_b32_e32 v6, 0x10000, v2
	v_mov_b32_e32 v7, v3
	v_or_b32_e32 v8, 0x18000, v2
	v_mov_b32_e32 v9, v3
	v_or_b32_e32 v10, 0x20000, v2
	v_mov_b32_e32 v11, v3
	v_or_b32_e32 v12, 0x28000, v2
	v_mov_b32_e32 v13, v3
	v_or_b32_e32 v14, 0x30000, v2
	v_mov_b32_e32 v15, v3
	v_or_b32_e32 v16, 0x38000, v2
	v_mov_b32_e32 v17, v3
	v_or_b32_e32 v2, 0x40000, v2
	v_lshl_add_u64 v[18:19], v[0:1], 0, 64
	s_mov_b64 s[8:9], 0x80
	v_lshl_add_u64 v[86:87], v[18:19], 0, v[4:5]
	v_lshl_add_u64 v[88:89], v[18:19], 0, v[6:7]
	v_lshl_add_u64 v[90:91], v[18:19], 0, v[8:9]
	v_lshl_add_u64 v[92:93], v[18:19], 0, v[10:11]
	v_lshl_add_u64 v[94:95], v[18:19], 0, v[12:13]
	v_lshl_add_u64 v[96:97], v[18:19], 0, v[14:15]
	v_lshl_add_u64 v[98:99], v[18:19], 0, v[16:17]
	v_lshl_add_u64 v[100:101], v[18:19], 0, v[2:3]
	v_lshl_add_u64 v[18:19], v[0:1], 0, s[8:9]
	s_mov_b64 s[8:9], 0xc0
	v_lshl_add_u64 v[74:75], v[0:1], 0, v[4:5]
	v_lshl_add_u64 v[76:77], v[0:1], 0, v[6:7]
	v_lshl_add_u64 v[78:79], v[0:1], 0, v[8:9]
	v_lshl_add_u64 v[80:81], v[0:1], 0, v[10:11]
	v_lshl_add_u64 v[82:83], v[0:1], 0, v[12:13]
	v_lshl_add_u64 v[84:85], v[0:1], 0, v[14:15]
	v_lshl_add_u64 v[118:119], v[0:1], 0, v[16:17]
	v_lshl_add_u64 v[120:121], v[0:1], 0, v[2:3]
	v_lshl_add_u64 v[0:1], v[0:1], 0, s[8:9]
	v_lshl_add_u64 v[122:123], v[0:1], 0, v[4:5]
	v_lshl_add_u64 v[124:125], v[0:1], 0, v[6:7]
	v_lshl_add_u64 v[126:127], v[0:1], 0, v[8:9]
	v_lshl_add_u64 v[128:129], v[0:1], 0, v[10:11]
	v_lshl_add_u64 v[130:131], v[0:1], 0, v[12:13]
	v_lshl_add_u64 v[132:133], v[0:1], 0, v[14:15]
	v_lshl_add_u64 v[134:135], v[0:1], 0, v[16:17]
	v_lshl_add_u64 v[136:137], v[0:1], 0, v[2:3]
	v_and_b32_e32 v0, 63, v141
	v_lshl_add_u64 v[116:117], v[18:19], 0, v[2:3]
	s_movk_i32 s10, 0x4800
	v_lshlrev_b32_e32 v2, 3, v152
	v_lshl_add_u32 v140, v0, 4, 16
	s_movk_i32 s6, 0x240
	s_movk_i32 s12, 0x6000
	v_lshl_add_u64 v[138:139], s[48:49], 0, v[2:3]
	s_mov_b64 s[76:77], s[48:49]
	v_or_b32_e32 v0, 32, v21
	v_or_b32_e32 v1, 64, v21
	v_or_b32_e32 v2, 0x60, v21
	v_mad_u64_u32 v[150:151], s[8:9], v20, s10, v[140:141]
	v_cmp_lt_i32_e64 s[0:1], 3, v20
	v_cmp_gt_i32_e64 s[4:5], 4, v20
	v_cmp_gt_i32_e64 s[6:7], s6, v141
	s_mov_b32 s13, 0x18000
	v_lshl_add_u64 v[102:103], v[18:19], 0, v[4:5]
	v_lshl_add_u64 v[104:105], v[18:19], 0, v[6:7]
	v_lshl_add_u64 v[106:107], v[18:19], 0, v[8:9]
	v_lshl_add_u64 v[108:109], v[18:19], 0, v[10:11]
	v_lshl_add_u64 v[110:111], v[18:19], 0, v[12:13]
	v_lshl_add_u64 v[112:113], v[18:19], 0, v[14:15]
	v_lshl_add_u64 v[114:115], v[18:19], 0, v[16:17]
	s_mov_b32 s30, 0xc000
	s_mov_b32 s31, 0x12000
	s_mov_b32 s33, 0x1e000
	s_mov_b32 s48, 0x24000
	s_mov_b32 s49, 0x2a000
	s_movk_i32 s52, 0x88
	s_mov_b32 s53, s2
	v_mad_i64_i32 v[142:143], s[8:9], v21, s12, 0
	v_lshl_add_u32 v171, v152, 3, v142
	v_mad_i64_i32 v[144:145], s[8:9], v0, s12, 0
	v_mad_i64_i32 v[146:147], s[8:9], v1, s12, 0
	v_mad_i64_i32 v[148:149], s[8:9], v2, s12, 0
	v_add_u32_e32 v151, 0xfffee000, v150
	v_add_u32_e32 v153, 0xffff0400, v150
	v_add_u32_e32 v154, 0xfffee400, v150
	v_add_u32_e32 v155, 0xffff0800, v150
	v_add_u32_e32 v156, 0xfffee800, v150
	v_add_u32_e32 v157, 0xffff0c00, v150
	v_add_u32_e32 v158, 0xfffeec00, v150
	v_add_u32_e32 v159, 0xffff1000, v150
	v_add_u32_e32 v160, 0xfffef000, v150
	v_add_u32_e32 v161, 0xffff1400, v150
	v_add_u32_e32 v162, 0xfffef400, v150
	v_add_u32_e32 v163, 0xffff1800, v150
	v_add_u32_e32 v164, 0xfffef800, v150
	v_add_u32_e32 v165, 0xffff1c00, v150
	v_add_u32_e32 v166, 0xfffefc00, v150
	v_add_u32_e32 v167, 0xffff2000, v150
	v_add_u32_e32 v168, 0xffff0000, v150
	v_add_u32_e32 v169, 0xffff2400, v150
	v_lshl_add_u32 v170, v141, 4, 16
	s_add_u32 s78, s58, 0xc8f0000
	s_addc_u32 s79, s59, 0
	v_and_b32_e32 v172, 63, v141
	v_lshlrev_b32_e32 v172, 4, v172
	v_lshl_or_b32 v172, v20, 12, v172
	v_mov_b32_e32 v173, 0
	v_lshl_add_u64 v[72:73], s[78:79], 0, v[172:173]
	s_mov_b64 s[78:79], 0x8000
	v_lshl_add_u64 v[74:75], v[72:73], 0, s[78:79]
	v_lshl_add_u64 v[76:77], v[74:75], 0, s[78:79]
	v_lshl_add_u64 v[78:79], v[76:77], 0, s[78:79]
	v_lshl_add_u64 v[80:81], v[78:79], 0, s[78:79]
	v_lshl_add_u64 v[82:83], v[80:81], 0, s[78:79]
	v_lshl_add_u64 v[84:85], v[82:83], 0, s[78:79]
	v_lshl_add_u64 v[118:119], v[84:85], 0, s[78:79]
	v_lshl_add_u64 v[120:121], v[118:119], 0, s[78:79]
	s_branch .LBB0_70

; __device__ __forceinline__ unsigned cvt_pk_bf16(float lo, float hi) { unsigned r; asm("v_cvt_pk_bf16_f32 %0, %1, %2" : "=v"(r) : "v"(lo), "v"(hi)); return r; }
; __device__ __forceinline__ void mod_phase(const Params& p, const bf16_t* __restrict__ Sb, float* smem) {
;     ...
;         for (int kk = 0; kk < 4; ++kk) { const float* wp = p.w_ada + (size_t)(w * 128 + kk * 32 + fq * 8) * NMOD + col0 + 2 * fr;
; #pragma unroll
;             for (int i = 0; i < 4; ++i) { const float2 v0 = *(const float2*)(wp + (size_t)(2 * i) * NMOD), v1 = *(const float2*)(wp + (size_t)(2 * i + 1) * NMOD);
;                 wfA[kk].u[i] = cvt_pk_bf16(v0.x, v1.x); wfB[kk].u[i] = cvt_pk_bf16(v0.y, v1.y); } }
; #pragma unroll
;         for (int kk = 0; kk < 4; ++kk) {
; #pragma unroll
;             for (int bt = 0; bt < 9; ++bt) { Frag sf; sf.q = *(const uint4*)(Sb + (size_t)(bt * 16 + fr) * DM + w * 128 + kk * 32 + fq * 8);
;                 acc[0][bt] = __builtin_amdgcn_mfma_f32_16x16x32_bf16(wfA[kk].v, sf.v, acc[0][bt], 0, 0, 0);
;                 acc[1][bt] = __builtin_amdgcn_mfma_f32_16x16x32_bf16(wfB[kk].v, sf.v, acc[1][bt], 0, 0, 0); } }
.LBB0_70:
	s_lshl_b32 s10, s53, 5
	s_ashr_i32 s11, s10, 31
	s_lshl_b32 s80, s53, 7
	s_add_u32 s78, s76, s80
	s_addc_u32 s79, s77, 0
	global_load_dwordx2 v[172:173], v171, s[78:79] nt
	s_add_u32 s78, s78, 0x6000
	s_addc_u32 s79, s79, 0
	global_load_dwordx2 v[174:175], v171, s[78:79] nt
	s_add_u32 s78, s78, 0x6000
	s_addc_u32 s79, s79, 0
	global_load_dwordx2 v[176:177], v171, s[78:79] nt
	s_add_u32 s78, s78, 0x6000
	s_addc_u32 s79, s79, 0
	global_load_dwordx2 v[178:179], v171, s[78:79] nt
	s_add_u32 s78, s78, 0x6000
	s_addc_u32 s79, s79, 0
	global_load_dwordx2 v[180:181], v171, s[78:79] nt
	s_add_u32 s78, s78, 0x6000
	s_addc_u32 s79, s79, 0
	global_load_dwordx2 v[182:183], v171, s[78:79] nt
	s_add_u32 s78, s78, 0x6000
	s_addc_u32 s79, s79, 0
	global_load_dwordx2 v[184:185], v171, s[78:79] nt
	s_add_u32 s78, s78, 0x6000
	s_addc_u32 s79, s79, 0
	global_load_dwordx2 v[186:187], v171, s[78:79] nt
	s_add_u32 s78, s78, 0x96000
	s_addc_u32 s79, s79, 0
	global_load_dwordx4 v[86:89], v[72:73], off
	global_load_dwordx4 v[90:93], v[74:75], off
	global_load_dwordx4 v[94:97], v[76:77], off
	global_load_dwordx4 v[98:101], v[78:79], off
	global_load_dwordx4 v[102:105], v[80:81], off
	global_load_dwordx4 v[106:109], v[82:83], off
	global_load_dwordx4 v[110:113], v[84:85], off
	global_load_dwordx4 v[114:117], v[118:119], off
	global_load_dwordx4 v[122:125], v[120:121], off
	global_load_dwordx2 v[188:189], v171, s[78:79] nt
	s_add_u32 s78, s78, 0x6000
	s_addc_u32 s79, s79, 0
	global_load_dwordx2 v[190:191], v171, s[78:79] nt
	s_add_u32 s78, s78, 0x6000
	s_addc_u32 s79, s79, 0
	global_load_dwordx2 v[192:193], v171, s[78:79] nt
	s_add_u32 s78, s78, 0x6000
	s_addc_u32 s79, s79, 0
	global_load_dwordx2 v[194:195], v171, s[78:79] nt
	s_add_u32 s78, s78, 0x6000
	s_addc_u32 s79, s79, 0
	global_load_dwordx2 v[196:197], v171, s[78:79] nt
	s_add_u32 s78, s78, 0x6000
	s_addc_u32 s79, s79, 0
	global_load_dwordx2 v[198:199], v171, s[78:79] nt
	s_add_u32 s78, s78, 0x6000
	s_addc_u32 s79, s79, 0
	global_load_dwordx2 v[200:201], v171, s[78:79] nt
	s_add_u32 s78, s78, 0x6000
	s_addc_u32 s79, s79, 0
	global_load_dwordx2 v[202:203], v171, s[78:79] nt
	s_add_u32 s78, s78, 0x96000
	s_addc_u32 s79, s79, 0
	global_load_dwordx2 v[204:205], v171, s[78:79] nt
	s_add_u32 s78, s78, 0x6000
	s_addc_u32 s79, s79, 0
	global_load_dwordx2 v[206:207], v171, s[78:79] nt
	s_add_u32 s78, s78, 0x6000
	s_addc_u32 s79, s79, 0
	global_load_dwordx2 v[208:209], v171, s[78:79] nt
	s_add_u32 s78, s78, 0x6000
	s_addc_u32 s79, s79, 0
	global_load_dwordx2 v[210:211], v171, s[78:79] nt
	s_add_u32 s78, s78, 0x6000
	s_addc_u32 s79, s79, 0
	global_load_dwordx2 v[212:213], v171, s[78:79] nt
	s_add_u32 s78, s78, 0x6000
	s_addc_u32 s79, s79, 0
	global_load_dwordx2 v[214:215], v171, s[78:79] nt
	s_add_u32 s78, s78, 0x6000
	s_addc_u32 s79, s79, 0
	global_load_dwordx2 v[216:217], v171, s[78:79] nt
	s_add_u32 s78, s78, 0x6000
	s_addc_u32 s79, s79, 0
	global_load_dwordx2 v[218:219], v171, s[78:79] nt
	s_add_u32 s78, s78, 0x96000
	s_addc_u32 s79, s79, 0
	global_load_dwordx2 v[220:221], v171, s[78:79] nt
	s_add_u32 s78, s78, 0x6000
	s_addc_u32 s79, s79, 0
	global_load_dwordx2 v[222:223], v171, s[78:79] nt
	s_add_u32 s78, s78, 0x6000
	s_addc_u32 s79, s79, 0
	global_load_dwordx2 v[226:227], v171, s[78:79] nt
	s_add_u32 s78, s78, 0x6000
	s_addc_u32 s79, s79, 0
	global_load_dwordx2 v[228:229], v171, s[78:79] nt
	s_add_u32 s78, s78, 0x6000
	s_addc_u32 s79, s79, 0
	global_load_dwordx2 v[230:231], v171, s[78:79] nt
	s_add_u32 s78, s78, 0x6000
	s_addc_u32 s79, s79, 0
	global_load_dwordx2 v[232:233], v171, s[78:79] nt
	s_add_u32 s78, s78, 0x6000
	s_addc_u32 s79, s79, 0
	global_load_dwordx2 v[234:235], v171, s[78:79] nt
	s_add_u32 s78, s78, 0x6000
	s_addc_u32 s79, s79, 0
	global_load_dwordx2 v[236:237], v171, s[78:79] nt
	s_waitcnt vmcnt(24)
	v_cvt_pk_bf16_f32 v126, v172, v174
	v_cvt_pk_bf16_f32 v130, v173, v175
	v_cvt_pk_bf16_f32 v127, v176, v178
	v_cvt_pk_bf16_f32 v131, v177, v179
	v_cvt_pk_bf16_f32 v128, v180, v182
	v_cvt_pk_bf16_f32 v132, v181, v183
	v_cvt_pk_bf16_f32 v129, v184, v186
	v_cvt_pk_bf16_f32 v133, v185, v187
	s_nop 1
	v_mfma_f32_16x16x32_bf16 v[0:3], v[126:129], v[86:89], 0
	v_mfma_f32_16x16x32_bf16 v[4:7], v[130:133], v[86:89], 0
	global_load_dwordx4 v[86:89], v[72:73], off offset:1024
	v_mfma_f32_16x16x32_bf16 v[16:19], v[126:129], v[90:93], 0
	v_mfma_f32_16x16x32_bf16 v[8:11], v[130:133], v[90:93], 0
	global_load_dwordx4 v[90:93], v[74:75], off offset:1024
	v_mfma_f32_16x16x32_bf16 v[12:15], v[126:129], v[94:97], 0
	v_mfma_f32_16x16x32_bf16 v[20:23], v[130:133], v[94:97], 0
	global_load_dwordx4 v[94:97], v[76:77], off offset:1024
	v_mfma_f32_16x16x32_bf16 v[32:35], v[126:129], v[98:101], 0
	v_mfma_f32_16x16x32_bf16 v[24:27], v[130:133], v[98:101], 0
	global_load_dwordx4 v[98:101], v[78:79], off offset:1024
	v_mfma_f32_16x16x32_bf16 v[28:31], v[126:129], v[102:105], 0
	v_mfma_f32_16x16x32_bf16 v[36:39], v[130:133], v[102:105], 0
	global_load_dwordx4 v[102:105], v[80:81], off offset:1024
	v_mfma_f32_16x16x32_bf16 v[48:51], v[126:129], v[106:109], 0
	v_mfma_f32_16x16x32_bf16 v[40:43], v[130:133], v[106:109], 0
	global_load_dwordx4 v[106:109], v[82:83], off offset:1024
	v_mfma_f32_16x16x32_bf16 v[44:47], v[126:129], v[110:113], 0
	v_mfma_f32_16x16x32_bf16 v[52:55], v[130:133], v[110:113], 0
	global_load_dwordx4 v[110:113], v[84:85], off offset:1024
	v_mfma_f32_16x16x32_bf16 v[68:71], v[126:129], v[114:117], 0
	v_mfma_f32_16x16x32_bf16 v[60:63], v[130:133], v[114:117], 0
	global_load_dwordx4 v[114:117], v[118:119], off offset:1024
	v_mfma_f32_16x16x32_bf16 v[64:67], v[126:129], v[122:125], 0
	v_mfma_f32_16x16x32_bf16 v[56:59], v[130:133], v[122:125], 0
	global_load_dwordx4 v[122:125], v[120:121], off offset:1024
	s_waitcnt vmcnt(8)
; __device__ __forceinline__ void mod_phase(const Params& p, const bf16_t* __restrict__ Sb, float* smem) {
;     ...
;         for (int kk = 0; kk < 4; ++kk) {
; #pragma unroll
;             for (int bt = 0; bt < 9; ++bt) { Frag sf; sf.q = *(const uint4*)(Sb + (size_t)(bt * 16 + fr) * DM + w * 128 + kk * 32 + fq * 8);
;                 acc[0][bt] = __builtin_amdgcn_mfma_f32_16x16x32_bf16(wfA[kk].v, sf.v, acc[0][bt], 0, 0, 0);
;                 acc[1][bt] = __builtin_amdgcn_mfma_f32_16x16x32_bf16(wfB[kk].v, sf.v, acc[1][bt], 0, 0, 0); } }
;         if (w >= 4) {
; #pragma unroll
;             for (int bt = 0; bt < 9; ++bt) { red[((w - 4) * 18 + bt) * 64 + lane] = acc[0][bt]; red[((w - 4) * 18 + 9 + bt) * 64 + lane] = acc[1][bt]; } }
;         __syncthreads();
	v_cvt_pk_bf16_f32 v126, v188, v190
	v_cvt_pk_bf16_f32 v130, v189, v191
	v_cvt_pk_bf16_f32 v127, v192, v194
	v_cvt_pk_bf16_f32 v131, v193, v195
	v_cvt_pk_bf16_f32 v128, v196, v198
	v_cvt_pk_bf16_f32 v132, v197, v199
	v_cvt_pk_bf16_f32 v129, v200, v202
	v_cvt_pk_bf16_f32 v133, v201, v203
	s_nop 1
	v_mfma_f32_16x16x32_bf16 v[0:3], v[126:129], v[86:89], v[0:3]
	v_mfma_f32_16x16x32_bf16 v[4:7], v[130:133], v[86:89], v[4:7]
	global_load_dwordx4 v[86:89], v[72:73], off offset:2048
	s_waitcnt vmcnt(8)
	v_mfma_f32_16x16x32_bf16 v[16:19], v[126:129], v[90:93], v[16:19]
	v_mfma_f32_16x16x32_bf16 v[8:11], v[130:133], v[90:93], v[8:11]
	global_load_dwordx4 v[90:93], v[74:75], off offset:2048
	s_waitcnt vmcnt(8)
	v_mfma_f32_16x16x32_bf16 v[12:15], v[126:129], v[94:97], v[12:15]
	v_mfma_f32_16x16x32_bf16 v[20:23], v[130:133], v[94:97], v[20:23]
	global_load_dwordx4 v[94:97], v[76:77], off offset:2048
	s_waitcnt vmcnt(8)
	v_mfma_f32_16x16x32_bf16 v[32:35], v[126:129], v[98:101], v[32:35]
	v_mfma_f32_16x16x32_bf16 v[24:27], v[130:133], v[98:101], v[24:27]
	global_load_dwordx4 v[98:101], v[78:79], off offset:2048
	s_waitcnt vmcnt(8)
	v_mfma_f32_16x16x32_bf16 v[28:31], v[126:129], v[102:105], v[28:31]
	v_mfma_f32_16x16x32_bf16 v[36:39], v[130:133], v[102:105], v[36:39]
	global_load_dwordx4 v[102:105], v[80:81], off offset:2048
	s_waitcnt vmcnt(8)
	v_mfma_f32_16x16x32_bf16 v[48:51], v[126:129], v[106:109], v[48:51]
	v_mfma_f32_16x16x32_bf16 v[40:43], v[130:133], v[106:109], v[40:43]
	global_load_dwordx4 v[106:109], v[82:83], off offset:2048
	s_waitcnt vmcnt(8)
	v_mfma_f32_16x16x32_bf16 v[44:47], v[126:129], v[110:113], v[44:47]
	v_mfma_f32_16x16x32_bf16 v[52:55], v[130:133], v[110:113], v[52:55]
	global_load_dwordx4 v[110:113], v[84:85], off offset:2048
	s_waitcnt vmcnt(8)
	v_mfma_f32_16x16x32_bf16 v[68:71], v[126:129], v[114:117], v[68:71]
	v_mfma_f32_16x16x32_bf16 v[60:63], v[130:133], v[114:117], v[60:63]
	global_load_dwordx4 v[114:117], v[118:119], off offset:2048
	s_waitcnt vmcnt(8)
	v_mfma_f32_16x16x32_bf16 v[64:67], v[126:129], v[122:125], v[64:67]
	v_mfma_f32_16x16x32_bf16 v[56:59], v[130:133], v[122:125], v[56:59]
	global_load_dwordx4 v[122:125], v[120:121], off offset:2048
	s_waitcnt vmcnt(8)
	v_cvt_pk_bf16_f32 v126, v204, v206
	v_cvt_pk_bf16_f32 v130, v205, v207
	v_cvt_pk_bf16_f32 v127, v208, v210
	v_cvt_pk_bf16_f32 v131, v209, v211
	v_cvt_pk_bf16_f32 v128, v212, v214
	v_cvt_pk_bf16_f32 v132, v213, v215
	v_cvt_pk_bf16_f32 v129, v216, v218
	v_cvt_pk_bf16_f32 v133, v217, v219
	s_nop 1
	v_mfma_f32_16x16x32_bf16 v[0:3], v[126:129], v[86:89], v[0:3]
	v_mfma_f32_16x16x32_bf16 v[4:7], v[130:133], v[86:89], v[4:7]
	global_load_dwordx4 v[86:89], v[72:73], off offset:3072
	s_waitcnt vmcnt(8)
	v_mfma_f32_16x16x32_bf16 v[16:19], v[126:129], v[90:93], v[16:19]
	v_mfma_f32_16x16x32_bf16 v[8:11], v[130:133], v[90:93], v[8:11]
	global_load_dwordx4 v[90:93], v[74:75], off offset:3072
	s_waitcnt vmcnt(8)
	v_mfma_f32_16x16x32_bf16 v[12:15], v[126:129], v[94:97], v[12:15]
	v_mfma_f32_16x16x32_bf16 v[20:23], v[130:133], v[94:97], v[20:23]
	global_load_dwordx4 v[94:97], v[76:77], off offset:3072
	s_waitcnt vmcnt(8)
	v_mfma_f32_16x16x32_bf16 v[32:35], v[126:129], v[98:101], v[32:35]
	v_mfma_f32_16x16x32_bf16 v[24:27], v[130:133], v[98:101], v[24:27]
	global_load_dwordx4 v[98:101], v[78:79], off offset:3072
	s_waitcnt vmcnt(8)
	v_mfma_f32_16x16x32_bf16 v[28:31], v[126:129], v[102:105], v[28:31]
	v_mfma_f32_16x16x32_bf16 v[36:39], v[130:133], v[102:105], v[36:39]
	global_load_dwordx4 v[102:105], v[80:81], off offset:3072
	s_waitcnt vmcnt(8)
	v_mfma_f32_16x16x32_bf16 v[48:51], v[126:129], v[106:109], v[48:51]
	v_mfma_f32_16x16x32_bf16 v[40:43], v[130:133], v[106:109], v[40:43]
	global_load_dwordx4 v[106:109], v[82:83], off offset:3072
	s_waitcnt vmcnt(8)
	v_mfma_f32_16x16x32_bf16 v[44:47], v[126:129], v[110:113], v[44:47]
	v_mfma_f32_16x16x32_bf16 v[52:55], v[130:133], v[110:113], v[52:55]
	global_load_dwordx4 v[110:113], v[84:85], off offset:3072
	s_waitcnt vmcnt(8)
	v_mfma_f32_16x16x32_bf16 v[68:71], v[126:129], v[114:117], v[68:71]
	v_mfma_f32_16x16x32_bf16 v[60:63], v[130:133], v[114:117], v[60:63]
	global_load_dwordx4 v[114:117], v[118:119], off offset:3072
	s_waitcnt vmcnt(8)
	v_mfma_f32_16x16x32_bf16 v[64:67], v[126:129], v[122:125], v[64:67]
	v_mfma_f32_16x16x32_bf16 v[56:59], v[130:133], v[122:125], v[56:59]
	global_load_dwordx4 v[122:125], v[120:121], off offset:3072
	s_waitcnt vmcnt(8)
	v_cvt_pk_bf16_f32 v126, v220, v222
	v_cvt_pk_bf16_f32 v130, v221, v223
	v_cvt_pk_bf16_f32 v127, v226, v228
	v_cvt_pk_bf16_f32 v131, v227, v229
	v_cvt_pk_bf16_f32 v128, v230, v232
	v_cvt_pk_bf16_f32 v132, v231, v233
	v_cvt_pk_bf16_f32 v129, v234, v236
	v_cvt_pk_bf16_f32 v133, v235, v237
	s_nop 1
	v_mfma_f32_16x16x32_bf16 v[0:3], v[126:129], v[86:89], v[0:3]
	v_mfma_f32_16x16x32_bf16 v[4:7], v[130:133], v[86:89], v[4:7]
	s_waitcnt vmcnt(7)
	v_mfma_f32_16x16x32_bf16 v[16:19], v[126:129], v[90:93], v[16:19]
	v_mfma_f32_16x16x32_bf16 v[8:11], v[130:133], v[90:93], v[8:11]
	s_waitcnt vmcnt(6)
	v_mfma_f32_16x16x32_bf16 v[12:15], v[126:129], v[94:97], v[12:15]
	v_mfma_f32_16x16x32_bf16 v[20:23], v[130:133], v[94:97], v[20:23]
	s_waitcnt vmcnt(5)
	v_mfma_f32_16x16x32_bf16 v[32:35], v[126:129], v[98:101], v[32:35]
	v_mfma_f32_16x16x32_bf16 v[24:27], v[130:133], v[98:101], v[24:27]
	s_waitcnt vmcnt(4)
	v_mfma_f32_16x16x32_bf16 v[28:31], v[126:129], v[102:105], v[28:31]
	v_mfma_f32_16x16x32_bf16 v[36:39], v[130:133], v[102:105], v[36:39]
	s_waitcnt vmcnt(3)
	v_mfma_f32_16x16x32_bf16 v[48:51], v[126:129], v[106:109], v[48:51]
	v_mfma_f32_16x16x32_bf16 v[40:43], v[130:133], v[106:109], v[40:43]
	s_waitcnt vmcnt(2)
	v_mfma_f32_16x16x32_bf16 v[44:47], v[126:129], v[110:113], v[44:47]
	v_mfma_f32_16x16x32_bf16 v[52:55], v[130:133], v[110:113], v[52:55]
	s_waitcnt vmcnt(1)
	v_mfma_f32_16x16x32_bf16 v[68:71], v[126:129], v[114:117], v[68:71]
	v_mfma_f32_16x16x32_bf16 v[60:63], v[130:133], v[114:117], v[60:63]
	s_waitcnt vmcnt(0)
	v_mfma_f32_16x16x32_bf16 v[64:67], v[126:129], v[122:125], v[64:67]
	v_mfma_f32_16x16x32_bf16 v[56:59], v[130:133], v[122:125], v[56:59]
	s_nop 7
	s_and_saveexec_b64 s[8:9], s[0:1]
	s_cbranch_execz .LBB0_72
	ds_write_b128 v151, v[0:3]
	ds_write_b128 v153, v[4:7]
	ds_write_b128 v154, v[16:19]
	ds_write_b128 v155, v[8:11]
	ds_write_b128 v156, v[12:15]
	ds_write_b128 v157, v[20:23]
	ds_write_b128 v158, v[32:35]
	ds_write_b128 v159, v[24:27]
	ds_write_b128 v160, v[28:31]
	ds_write_b128 v161, v[36:39]
	ds_write_b128 v162, v[48:51]
	ds_write_b128 v163, v[40:43]
	ds_write_b128 v164, v[44:47]
	ds_write_b128 v165, v[52:55]
	ds_write_b128 v166, v[68:71]
	ds_write_b128 v167, v[60:63]
	ds_write_b128 v168, v[64:67]
	ds_write_b128 v169, v[56:59]
